# prep rope loop: k_norm weights loaded once before the loop
# speedup vs baseline: 1.0040x; 1.0040x over previous
; DEVI int opaque_tid(int wv) { int ln; asm volatile("v_mbcnt_lo_u32_b32 %0, -1, 0\n\tv_mbcnt_hi_u32_b32 %0, -1, %0" : "=v"(ln)); return wv * 64 + ln; }
; DEVI void unpack8(const u32x4 w, float (&v)[8]) { v[0] = bflo(w.x); v[1] = bfhi(w.x); v[2] = bflo(w.y); v[3] = bfhi(w.y); v[4] = bflo(w.z); v[5] = bfhi(w.z); v[6] = bflo(w.w); v[7] = bfhi(w.w); }
; DEVI void ph_prep(const int wv, const Params& p, int l, int nrows_pool, unsigned char* lds_raw) {
;     const int tid = opaque_tid(wv); const int lane = tid & 63;
;     bf16_t* Z = (bf16_t*)(p.ws + OFF_ZG); bf16_t* YB = (bf16_t*)(p.ws + OFF_YB);
;     const float* RTf = (const float*)(p.ws + OFF_RT); const float* ATf = (const float*)(p.ws + OFF_AT);
;     const int sub = lane & 7, hslot = lane >> 3, d0 = sub * 8;
;     constexpr int NINST = RT_ * 6;
;     for (int base = (blockIdx.x * 8 + wv) * 32; base < NINST; base += gridDim.x * 8 * 32) {
;         u32x4 w[4]; int rowv[4], hhv[4], colv[4];
; #pragma unroll
;         for (int u = 0; u < 4; ++u) { const int hi = base + u * 8 + hslot; const int row = hi / 6, h6 = hi - row * 6, hh = h6 < 4 ? h6 : h6 + 4; rowv[u] = row; hhv[u] = hh;
;             colv[u] = (hh < 4 ? C_RK + hh * 64 : hh < 8 ? C_RQ + (hh - 4) * 64 : hh < 10 ? C_AK + (hh - 8) * 64 : C_AQ + (hh - 10) * 64) + d0;
;             w[u] = *(const u32x4*)(Z + (size_t)row * ZM + colv[u]); }
; #pragma unroll
;         for (int u = 0; u < 4; ++u) {
;             const int row = rowv[u], hh = hhv[u]; const bool lat = row < NLAT; const int pos = row & 2047;
;             float v[8]; unpack8(w[u], v);
;             if (hh >= 8) {
;                 float ss = 0.f;
; #pragma unroll
;                 for (int e = 0; e < 8; ++e) ss += v[e] * v[e];
;                 ss += __shfl_xor(ss, 1); ss += __shfl_xor(ss, 2); ss += __shfl_xor(ss, 4);
;                 const float rstd = rsqrtf(ss * (1.0f / 64.0f) + EPS) * (hh >= 10 ? 0.125f * 1.4426950408889634f : 1.0f);
;                 const float* wp = p.in[hh < 10 ? 13 : 12] + l * 64 + d0;
;                 const f32x4 w0 = *(const f32x4*)wp, w1 = *(const f32x4*)(wp + 4);
.LBB0_377:
	s_andn2_b64 vcc, exec, s[0:1]
	s_cbranch_vccnz .LBB0_536
	v_readlane_b32 s0, v252, 22
	v_readlane_b32 s1, v252, 23
	s_andn2_b64 vcc, exec, s[0:1]
	v_mbcnt_lo_u32_b32 v19, -1, 0
	v_mbcnt_hi_u32_b32 v19, -1, v19
	s_cbranch_vccnz .LBB0_469
	v_and_b32_e32 v0, 7, v19
	v_lshlrev_b32_e32 v18, 3, v0
	v_lshlrev_b32_e32 v0, 4, v0
	v_and_b32_e32 v29, 48, v0
	s_waitcnt lgkmcnt(0)
	v_and_b32_e32 v2, 4, v19
	v_readlane_b32 s0, v253, 31
	v_and_b32_e32 v42, 16, v0
	v_and_b32_e32 v0, 2, v19
	v_bfe_u32 v25, v19, 3, 3
	v_cmp_eq_u32_e32 vcc, 0, v2
	s_lshl_b32 s18, s0, 6
	v_cmp_eq_u32_e64 s[0:1], 0, v0
	v_readlane_b32 s36, v252, 21
	v_lshlrev_b32_e32 v66, 2, v18
	v_mov_b32_e32 v67, 0
	v_lshl_add_u64 v[66:67], s[18:19], 2, v[66:67]
	v_lshl_add_u64 v[66:67], s[86:87], 0, v[66:67]
	global_load_dwordx4 v[70:73], v[66:67], off
	global_load_dwordx4 v[74:77], v[66:67], off offset:16
	s_waitcnt vmcnt(0)
	s_branch .LBB0_382

; DEVI void ph_prep(const int wv, const Params& p, int l, int nrows_pool, unsigned char* lds_raw) {
;     ...
;             if (hh >= 8) {
;                 float ss = 0.f;
; #pragma unroll
;                 for (int e = 0; e < 8; ++e) ss += v[e] * v[e];
;                 ss += __shfl_xor(ss, 1); ss += __shfl_xor(ss, 2); ss += __shfl_xor(ss, 4);
;                 const float rstd = rsqrtf(ss * (1.0f / 64.0f) + EPS) * (hh >= 10 ? 0.125f * 1.4426950408889634f : 1.0f);
;                 const float* wp = p.in[hh < 10 ? 13 : 12] + l * 64 + d0;
;                 const f32x4 w0 = *(const f32x4*)wp, w1 = *(const f32x4*)(wp + 4);
; #pragma unroll
;                 for (int e = 0; e < 4; ++e) { v[e] *= rstd * w0[e]; v[4 + e] *= rstd * w1[e]; }
;                 if (lat) { const int pp = (sub & 4) ? (pos & 63) : (pos >> 6); const float* cp = ATf + (size_t)(pp * 16 + (d0 & 15)) * 2; const bool up = (sub & 2) != 0;
; #pragma unroll
;                     for (int e = 0; e < 8; ++e) { const float o = __shfl_xor(v[e], 2); const float cc = cp[2 * e], sn = cp[2 * e + 1]; v[e] = up ? o * sn + v[e] * cc : v[e] * cc - o * sn; } }
.LBB0_436:
	s_or_saveexec_b64 s[12:13], s[28:29]
	v_lshlrev_b32_e32 v0, 2, v18
	s_xor_b64 exec, exec, s[12:13]
	s_cbranch_execz .LBB0_440
	v_pk_mul_f32 v[14:15], v[34:35], v[34:35]
	v_pk_mul_f32 v[16:17], v[36:37], v[36:37]
	v_add_f32_e32 v14, v14, v15
	v_add_f32_e32 v14, v16, v14
	v_pk_mul_f32 v[52:53], v[38:39], v[38:39]
	v_add_f32_e32 v14, v17, v14
	v_add_f32_e32 v14, v52, v14
	v_xor_b32_e32 v15, 1, v225
	v_pk_mul_f32 v[54:55], v[40:41], v[40:41]
	v_add_f32_e32 v14, v53, v14
	v_cmp_lt_i32_e64 s[10:11], v15, v226
	v_add_f32_e32 v14, v54, v14
	v_add_f32_e32 v14, v55, v14
	v_cndmask_b32_e64 v15, v225, v15, s[10:11]
	v_lshlrev_b32_e32 v15, 2, v15
	ds_bpermute_b32 v15, v15, v14
	v_mov_b32_e32 v16, s87
	s_waitcnt lgkmcnt(0)
	v_add_f32_e32 v14, v14, v15
	v_xor_b32_e32 v15, 2, v225
	v_cmp_lt_i32_e64 s[10:11], v15, v226
	s_nop 1
	v_cndmask_b32_e64 v15, v225, v15, s[10:11]
	v_lshlrev_b32_e32 v49, 2, v15
	ds_bpermute_b32 v15, v49, v14
	s_waitcnt lgkmcnt(0)
	v_add_f32_e32 v14, v14, v15
	v_xor_b32_e32 v15, 4, v225
	v_cmp_lt_i32_e64 s[10:11], v15, v226
	s_nop 1
	v_cndmask_b32_e64 v15, v225, v15, s[10:11]
	v_lshlrev_b32_e32 v15, 2, v15
	ds_bpermute_b32 v15, v15, v14
	s_mov_b32 s10, 0x800000
	s_waitcnt lgkmcnt(0)
	v_add_f32_e32 v14, v14, v15
	v_fmamk_f32 v14, v14, 0x3c800000, v196
	v_cmp_gt_f32_e64 s[10:11], s10, v14
	v_mul_f32_e32 v15, 0x4b800000, v14
	s_nop 0
	v_cndmask_b32_e64 v14, v14, v15, s[10:11]
	v_rsq_f32_e32 v14, v14
	s_nop 0
	v_mul_f32_e32 v15, 0x45800000, v14
	v_cndmask_b32_e64 v14, v14, v15, s[10:11]
	v_cmp_lt_u32_e64 s[10:11], 9, v51
	s_nop 1
	v_cndmask_b32_e64 v15, 1.0, v231, s[10:11]
	v_mul_f32_e32 v14, v15, v14
	v_cmp_gt_u32_e64 s[10:11], 10, v51
	v_mov_b32_e32 v15, s85
	s_nop 0
	v_cndmask_b32_e64 v17, v15, v16, s[10:11]
	v_mov_b32_e32 v15, s84
	v_mov_b32_e32 v16, s86
	v_cndmask_b32_e64 v16, v15, v16, s[10:11]
	v_lshl_add_u64 v[16:17], s[18:19], 2, v[16:17]
	v_lshl_add_u64 v[16:17], v[16:17], 0, v[0:1]
	v_mov_b32_e32 v52, v74
	v_mov_b32_e32 v53, v75
	v_mov_b32_e32 v54, v76
	v_mov_b32_e32 v55, v77
	v_mov_b32_e32 v56, v70
	v_mov_b32_e32 v57, v71
	v_mov_b32_e32 v58, v72
	v_mov_b32_e32 v59, v73
	s_waitcnt vmcnt(0)
	v_pk_mul_f32 v[16:17], v[56:57], v[14:15] op_sel_hi:[1,0]
	s_nop 0
	v_pk_mul_f32 v[34:35], v[16:17], v[34:35]
	v_pk_mul_f32 v[16:17], v[52:53], v[14:15] op_sel_hi:[1,0]
	s_nop 0
	v_pk_mul_f32 v[38:39], v[16:17], v[38:39]
	v_pk_mul_f32 v[16:17], v[58:59], v[14:15] op_sel_hi:[1,0]
	v_pk_mul_f32 v[14:15], v[54:55], v[14:15] op_sel_hi:[1,0]
	v_pk_mul_f32 v[36:37], v[16:17], v[36:37]
	v_pk_mul_f32 v[40:41], v[14:15], v[40:41]
	s_and_saveexec_b64 s[10:11], s[8:9]
	s_cbranch_execz .LBB0_439
	v_and_b32_e32 v14, 63, v33
	v_lshrrev_b32_e32 v15, 6, v50
	v_cndmask_b32_e32 v14, v14, v15, vcc
	v_lshlrev_b32_e32 v15, 2, v42
	v_readlane_b32 s8, v252, 19
	v_lshl_or_b32 v33, v14, 7, v15
	v_readlane_b32 s9, v252, 20
	s_nop 4
	global_load_dwordx4 v[14:17], v33, s[8:9] offset:48
	global_load_dwordx4 v[50:53], v33, s[8:9] offset:32
	global_load_dwordx4 v[54:57], v33, s[8:9] offset:16
	global_load_dwordx4 v[58:61], v33, s[8:9]
	ds_bpermute_b32 v62, v49, v34
	ds_bpermute_b32 v63, v49, v35
	s_waitcnt vmcnt(0)
	v_mov_b32_e32 v64, v59
	v_mov_b32_e32 v65, v61
	s_waitcnt lgkmcnt(0)
	v_pk_mul_f32 v[62:63], v[64:65], v[62:63]
	v_mov_b32_e32 v59, v60
	v_cndmask_b32_e64 v61, v63, -v63, s[0:1]
	v_cndmask_b32_e64 v60, v62, -v62, s[0:1]
	v_pk_fma_f32 v[34:35], v[34:35], v[58:59], v[60:61]
	ds_bpermute_b32 v58, v49, v36
	ds_bpermute_b32 v59, v49, v37
	v_mov_b32_e32 v60, v55
	v_mov_b32_e32 v61, v57
	v_mov_b32_e32 v55, v56
	s_waitcnt lgkmcnt(0)
	v_pk_mul_f32 v[58:59], v[60:61], v[58:59]
	s_nop 0
	v_cndmask_b32_e64 v57, v59, -v59, s[0:1]
	v_cndmask_b32_e64 v56, v58, -v58, s[0:1]
	v_pk_fma_f32 v[36:37], v[36:37], v[54:55], v[56:57]
	ds_bpermute_b32 v54, v49, v38
	ds_bpermute_b32 v55, v49, v39
	v_mov_b32_e32 v56, v51
	v_mov_b32_e32 v57, v53
	v_mov_b32_e32 v51, v52
	s_waitcnt lgkmcnt(0)
	v_pk_mul_f32 v[54:55], v[56:57], v[54:55]
	s_nop 0
	v_cndmask_b32_e64 v53, v55, -v55, s[0:1]
	v_cndmask_b32_e64 v52, v54, -v54, s[0:1]
	v_pk_fma_f32 v[38:39], v[38:39], v[50:51], v[52:53]
	ds_bpermute_b32 v50, v49, v40
	ds_bpermute_b32 v51, v49, v41
	v_mov_b32_e32 v52, v15
	v_mov_b32_e32 v53, v17
	v_mov_b32_e32 v15, v16
	s_waitcnt lgkmcnt(0)
	v_pk_mul_f32 v[50:51], v[52:53], v[50:51]
	s_nop 0
	v_cndmask_b32_e64 v17, v51, -v51, s[0:1]
	v_cndmask_b32_e64 v16, v50, -v50, s[0:1]
	v_pk_fma_f32 v[40:41], v[40:41], v[14:15], v[16:17]

; DEVI void ph_prep(const int wv, const Params& p, int l, int nrows_pool, unsigned char* lds_raw) {
;     ...
;             if (hh >= 8) {
;                 float ss = 0.f;
; #pragma unroll
;                 for (int e = 0; e < 8; ++e) ss += v[e] * v[e];
;                 ss += __shfl_xor(ss, 1); ss += __shfl_xor(ss, 2); ss += __shfl_xor(ss, 4);
;                 const float rstd = rsqrtf(ss * (1.0f / 64.0f) + EPS) * (hh >= 10 ? 0.125f * 1.4426950408889634f : 1.0f);
;                 const float* wp = p.in[hh < 10 ? 13 : 12] + l * 64 + d0;
;                 const f32x4 w0 = *(const f32x4*)wp, w1 = *(const f32x4*)(wp + 4);
; #pragma unroll
;                 for (int e = 0; e < 4; ++e) { v[e] *= rstd * w0[e]; v[4 + e] *= rstd * w1[e]; }
;                 if (lat) { const int pp = (sub & 4) ? (pos & 63) : (pos >> 6); const float* cp = ATf + (size_t)(pp * 16 + (d0 & 15)) * 2; const bool up = (sub & 2) != 0;
; #pragma unroll
;                     for (int e = 0; e < 8; ++e) { const float o = __shfl_xor(v[e], 2); const float cc = cp[2 * e], sn = cp[2 * e + 1]; v[e] = up ? o * sn + v[e] * cc : v[e] * cc - o * sn; } }
.LBB0_446:
	s_andn2_saveexec_b64 s[10:11], s[12:13]
	s_cbranch_execz .LBB0_450
	v_pk_mul_f32 v[10:11], v[14:15], v[14:15]
	v_pk_mul_f32 v[12:13], v[16:17], v[16:17]
	v_add_f32_e32 v10, v10, v11
	v_add_f32_e32 v10, v12, v10
	v_pk_mul_f32 v[36:37], v[30:31], v[30:31]
	v_add_f32_e32 v10, v13, v10
	v_add_f32_e32 v10, v36, v10
	v_xor_b32_e32 v11, 1, v225
	v_pk_mul_f32 v[38:39], v[32:33], v[32:33]
	v_add_f32_e32 v10, v37, v10
	v_cmp_lt_i32_e64 s[6:7], v11, v226
	v_add_f32_e32 v10, v38, v10
	v_add_f32_e32 v10, v39, v10
	v_cndmask_b32_e64 v11, v225, v11, s[6:7]
	v_lshlrev_b32_e32 v11, 2, v11
	ds_bpermute_b32 v11, v11, v10
	v_mov_b32_e32 v12, s87
	s_waitcnt lgkmcnt(0)
	v_add_f32_e32 v10, v10, v11
	v_xor_b32_e32 v11, 2, v225
	v_cmp_lt_i32_e64 s[6:7], v11, v226
	s_nop 1
	v_cndmask_b32_e64 v11, v225, v11, s[6:7]
	v_lshlrev_b32_e32 v34, 2, v11
	ds_bpermute_b32 v11, v34, v10
	s_waitcnt lgkmcnt(0)
	v_add_f32_e32 v10, v10, v11
	v_xor_b32_e32 v11, 4, v225
	v_cmp_lt_i32_e64 s[6:7], v11, v226
	s_nop 1
	v_cndmask_b32_e64 v11, v225, v11, s[6:7]
	v_lshlrev_b32_e32 v11, 2, v11
	ds_bpermute_b32 v11, v11, v10
	s_mov_b32 s6, 0x800000
	s_waitcnt lgkmcnt(0)
	v_add_f32_e32 v10, v10, v11
	v_fmamk_f32 v10, v10, 0x3c800000, v196
	v_cmp_gt_f32_e64 s[6:7], s6, v10
	v_mul_f32_e32 v11, 0x4b800000, v10
	s_nop 0
	v_cndmask_b32_e64 v10, v10, v11, s[6:7]
	v_rsq_f32_e32 v10, v10
	s_nop 0
	v_mul_f32_e32 v11, 0x45800000, v10
	v_cndmask_b32_e64 v10, v10, v11, s[6:7]
	v_cmp_lt_u32_e64 s[6:7], 9, v48
	s_nop 1
	v_cndmask_b32_e64 v11, 1.0, v231, s[6:7]
	v_mul_f32_e32 v10, v11, v10
	v_cmp_gt_u32_e64 s[6:7], 10, v48
	v_mov_b32_e32 v11, s85
	s_nop 0
	v_cndmask_b32_e64 v13, v11, v12, s[6:7]
	v_mov_b32_e32 v11, s84
	v_mov_b32_e32 v12, s86
	v_cndmask_b32_e64 v12, v11, v12, s[6:7]
	v_lshl_add_u64 v[12:13], s[18:19], 2, v[12:13]
	v_lshl_add_u64 v[12:13], v[12:13], 0, v[0:1]
	v_mov_b32_e32 v36, v74
	v_mov_b32_e32 v37, v75
	v_mov_b32_e32 v38, v76
	v_mov_b32_e32 v39, v77
	v_mov_b32_e32 v48, v70
	v_mov_b32_e32 v49, v71
	v_mov_b32_e32 v50, v72
	v_mov_b32_e32 v51, v73
	s_waitcnt vmcnt(0)
	v_pk_mul_f32 v[12:13], v[48:49], v[10:11] op_sel_hi:[1,0]
	s_nop 0
	v_pk_mul_f32 v[14:15], v[12:13], v[14:15]
	v_pk_mul_f32 v[12:13], v[36:37], v[10:11] op_sel_hi:[1,0]
	s_nop 0
	v_pk_mul_f32 v[30:31], v[12:13], v[30:31]
	v_pk_mul_f32 v[12:13], v[50:51], v[10:11] op_sel_hi:[1,0]
	v_pk_mul_f32 v[10:11], v[38:39], v[10:11] op_sel_hi:[1,0]
	v_pk_mul_f32 v[16:17], v[12:13], v[16:17]
	v_pk_mul_f32 v[32:33], v[10:11], v[32:33]
	s_and_saveexec_b64 s[6:7], s[8:9]
	s_cbranch_execz .LBB0_449
	v_and_b32_e32 v10, 63, v47
	v_lshrrev_b32_e32 v11, 6, v35
	v_cndmask_b32_e32 v10, v10, v11, vcc
	v_lshlrev_b32_e32 v11, 2, v42
	v_readlane_b32 s8, v252, 19
	v_lshl_or_b32 v35, v10, 7, v11
	v_readlane_b32 s9, v252, 20
	s_nop 4
	global_load_dwordx4 v[10:13], v35, s[8:9] offset:48
	global_load_dwordx4 v[36:39], v35, s[8:9] offset:32
	global_load_dwordx4 v[48:51], v35, s[8:9] offset:16
	global_load_dwordx4 v[52:55], v35, s[8:9]
	ds_bpermute_b32 v40, v34, v14
	ds_bpermute_b32 v41, v34, v15
	s_waitcnt vmcnt(3)
	v_mov_b32_e32 v35, v13
	s_waitcnt vmcnt(0)
	v_mov_b32_e32 v56, v53
	v_mov_b32_e32 v57, v55
	s_waitcnt lgkmcnt(0)
	v_pk_mul_f32 v[40:41], v[56:57], v[40:41]
	v_mov_b32_e32 v53, v54
	v_cndmask_b32_e64 v41, v41, -v41, s[0:1]
	v_cndmask_b32_e64 v40, v40, -v40, s[0:1]
	v_pk_fma_f32 v[14:15], v[14:15], v[52:53], v[40:41]
	ds_bpermute_b32 v40, v34, v16
	ds_bpermute_b32 v41, v34, v17
	v_mov_b32_e32 v52, v49
	v_mov_b32_e32 v53, v51
	v_mov_b32_e32 v49, v50
	s_waitcnt lgkmcnt(0)
	v_pk_mul_f32 v[40:41], v[52:53], v[40:41]
	s_nop 0
	v_cndmask_b32_e64 v41, v41, -v41, s[0:1]
	v_cndmask_b32_e64 v40, v40, -v40, s[0:1]
	v_pk_fma_f32 v[16:17], v[16:17], v[48:49], v[40:41]
	ds_bpermute_b32 v40, v34, v30
	ds_bpermute_b32 v41, v34, v31
	v_mov_b32_e32 v48, v37
	v_mov_b32_e32 v49, v39
	v_mov_b32_e32 v37, v38
	s_waitcnt lgkmcnt(0)
	v_pk_mul_f32 v[40:41], v[48:49], v[40:41]
	s_nop 0
	v_cndmask_b32_e64 v39, v41, -v41, s[0:1]
	v_cndmask_b32_e64 v38, v40, -v40, s[0:1]
	v_pk_fma_f32 v[30:31], v[30:31], v[36:37], v[38:39]
	ds_bpermute_b32 v36, v34, v32
	ds_bpermute_b32 v37, v34, v33
	v_mov_b32_e32 v34, v11
	v_mov_b32_e32 v11, v12
	s_waitcnt lgkmcnt(0)
	v_pk_mul_f32 v[34:35], v[34:35], v[36:37]
	s_nop 0
	v_cndmask_b32_e64 v13, v35, -v35, s[0:1]
	v_cndmask_b32_e64 v12, v34, -v34, s[0:1]
	v_pk_fma_f32 v[32:33], v[32:33], v[10:11], v[12:13]

; DEVI void ph_prep(const int wv, const Params& p, int l, int nrows_pool, unsigned char* lds_raw) {
;     ...
;             if (hh >= 8) {
;                 float ss = 0.f;
; #pragma unroll
;                 for (int e = 0; e < 8; ++e) ss += v[e] * v[e];
;                 ss += __shfl_xor(ss, 1); ss += __shfl_xor(ss, 2); ss += __shfl_xor(ss, 4);
;                 const float rstd = rsqrtf(ss * (1.0f / 64.0f) + EPS) * (hh >= 10 ? 0.125f * 1.4426950408889634f : 1.0f);
;                 const float* wp = p.in[hh < 10 ? 13 : 12] + l * 64 + d0;
;                 const f32x4 w0 = *(const f32x4*)wp, w1 = *(const f32x4*)(wp + 4);
; #pragma unroll
;                 for (int e = 0; e < 4; ++e) { v[e] *= rstd * w0[e]; v[4 + e] *= rstd * w1[e]; }
;                 if (lat) { const int pp = (sub & 4) ? (pos & 63) : (pos >> 6); const float* cp = ATf + (size_t)(pp * 16 + (d0 & 15)) * 2; const bool up = (sub & 2) != 0;
; #pragma unroll
;                     for (int e = 0; e < 8; ++e) { const float o = __shfl_xor(v[e], 2); const float cc = cp[2 * e], sn = cp[2 * e + 1]; v[e] = up ? o * sn + v[e] * cc : v[e] * cc - o * sn; } }
.LBB0_456:
	s_andn2_saveexec_b64 s[8:9], s[10:11]
	s_cbranch_execz .LBB0_460
	v_pk_mul_f32 v[6:7], v[10:11], v[10:11]
	v_pk_mul_f32 v[8:9], v[12:13], v[12:13]
	v_add_f32_e32 v6, v6, v7
	v_add_f32_e32 v6, v8, v6
	v_pk_mul_f32 v[30:31], v[14:15], v[14:15]
	v_add_f32_e32 v6, v9, v6
	v_add_f32_e32 v6, v30, v6
	v_xor_b32_e32 v7, 1, v225
	v_pk_mul_f32 v[32:33], v[16:17], v[16:17]
	v_add_f32_e32 v6, v31, v6
	v_cmp_lt_i32_e64 s[4:5], v7, v226
	v_add_f32_e32 v6, v32, v6
	v_add_f32_e32 v6, v33, v6
	v_cndmask_b32_e64 v7, v225, v7, s[4:5]
	v_lshlrev_b32_e32 v7, 2, v7
	ds_bpermute_b32 v7, v7, v6
	v_mov_b32_e32 v8, s87
	s_waitcnt lgkmcnt(0)
	v_add_f32_e32 v6, v6, v7
	v_xor_b32_e32 v7, 2, v225
	v_cmp_lt_i32_e64 s[4:5], v7, v226
	s_nop 1
	v_cndmask_b32_e64 v7, v225, v7, s[4:5]
	v_lshlrev_b32_e32 v26, 2, v7
	ds_bpermute_b32 v7, v26, v6
	s_waitcnt lgkmcnt(0)
	v_add_f32_e32 v6, v6, v7
	v_xor_b32_e32 v7, 4, v225
	v_cmp_lt_i32_e64 s[4:5], v7, v226
	s_nop 1
	v_cndmask_b32_e64 v7, v225, v7, s[4:5]
	v_lshlrev_b32_e32 v7, 2, v7
	ds_bpermute_b32 v7, v7, v6
	s_mov_b32 s4, 0x800000
	s_waitcnt lgkmcnt(0)
	v_add_f32_e32 v6, v6, v7
	v_fmamk_f32 v6, v6, 0x3c800000, v196
	v_cmp_gt_f32_e64 s[4:5], s4, v6
	v_mul_f32_e32 v7, 0x4b800000, v6
	s_nop 0
	v_cndmask_b32_e64 v6, v6, v7, s[4:5]
	v_rsq_f32_e32 v6, v6
	s_nop 0
	v_mul_f32_e32 v7, 0x45800000, v6
	v_cndmask_b32_e64 v6, v6, v7, s[4:5]
	v_cmp_lt_u32_e64 s[4:5], 9, v46
	s_nop 1
	v_cndmask_b32_e64 v7, 1.0, v231, s[4:5]
	v_mul_f32_e32 v6, v7, v6
	v_cmp_gt_u32_e64 s[4:5], 10, v46
	v_mov_b32_e32 v7, s85
	s_nop 0
	v_cndmask_b32_e64 v9, v7, v8, s[4:5]
	v_mov_b32_e32 v7, s84
	v_mov_b32_e32 v8, s86
	v_cndmask_b32_e64 v8, v7, v8, s[4:5]
	v_lshl_add_u64 v[8:9], s[18:19], 2, v[8:9]
	v_lshl_add_u64 v[8:9], v[8:9], 0, v[0:1]
	v_mov_b32_e32 v30, v74
	v_mov_b32_e32 v31, v75
	v_mov_b32_e32 v32, v76
	v_mov_b32_e32 v33, v77
	v_mov_b32_e32 v34, v70
	v_mov_b32_e32 v35, v71
	v_mov_b32_e32 v36, v72
	v_mov_b32_e32 v37, v73
	s_waitcnt vmcnt(0)
	v_pk_mul_f32 v[8:9], v[34:35], v[6:7] op_sel_hi:[1,0]
	s_nop 0
	v_pk_mul_f32 v[10:11], v[8:9], v[10:11]
	v_pk_mul_f32 v[8:9], v[30:31], v[6:7] op_sel_hi:[1,0]
	s_nop 0
	v_pk_mul_f32 v[14:15], v[8:9], v[14:15]
	v_pk_mul_f32 v[8:9], v[36:37], v[6:7] op_sel_hi:[1,0]
	v_pk_mul_f32 v[6:7], v[32:33], v[6:7] op_sel_hi:[1,0]
	v_pk_mul_f32 v[12:13], v[8:9], v[12:13]
	v_pk_mul_f32 v[16:17], v[6:7], v[16:17]
	s_and_saveexec_b64 s[4:5], s[6:7]
	s_cbranch_execz .LBB0_459
	v_and_b32_e32 v6, 63, v45
	v_lshrrev_b32_e32 v7, 6, v27
	v_cndmask_b32_e32 v6, v6, v7, vcc
	v_lshlrev_b32_e32 v7, 2, v42
	v_readlane_b32 s6, v252, 19
	v_lshl_or_b32 v27, v6, 7, v7
	v_readlane_b32 s7, v252, 20
	s_nop 4
	global_load_dwordx4 v[6:9], v27, s[6:7] offset:48
	global_load_dwordx4 v[30:33], v27, s[6:7] offset:32
	global_load_dwordx4 v[34:37], v27, s[6:7] offset:16
	global_load_dwordx4 v[38:41], v27, s[6:7]
	ds_bpermute_b32 v46, v26, v10
	ds_bpermute_b32 v47, v26, v11
	s_waitcnt vmcnt(3)
	v_mov_b32_e32 v27, v9
	s_waitcnt vmcnt(0)
	v_mov_b32_e32 v48, v39
	v_mov_b32_e32 v49, v41
	s_waitcnt lgkmcnt(0)
	v_pk_mul_f32 v[46:47], v[48:49], v[46:47]
	v_mov_b32_e32 v39, v40
	v_cndmask_b32_e64 v41, v47, -v47, s[0:1]
	v_cndmask_b32_e64 v40, v46, -v46, s[0:1]
	v_pk_fma_f32 v[10:11], v[10:11], v[38:39], v[40:41]
	ds_bpermute_b32 v38, v26, v12
	ds_bpermute_b32 v39, v26, v13
	v_mov_b32_e32 v40, v35
	v_mov_b32_e32 v41, v37
	v_mov_b32_e32 v35, v36
	s_waitcnt lgkmcnt(0)
	v_pk_mul_f32 v[38:39], v[40:41], v[38:39]
	s_nop 0
	v_cndmask_b32_e64 v37, v39, -v39, s[0:1]
	v_cndmask_b32_e64 v36, v38, -v38, s[0:1]
	v_pk_fma_f32 v[12:13], v[12:13], v[34:35], v[36:37]
	ds_bpermute_b32 v34, v26, v14
	ds_bpermute_b32 v35, v26, v15
	v_mov_b32_e32 v36, v31
	v_mov_b32_e32 v37, v33
	v_mov_b32_e32 v31, v32
	s_waitcnt lgkmcnt(0)
	v_pk_mul_f32 v[34:35], v[36:37], v[34:35]
	s_nop 0
	v_cndmask_b32_e64 v33, v35, -v35, s[0:1]
	v_cndmask_b32_e64 v32, v34, -v34, s[0:1]
	v_pk_fma_f32 v[14:15], v[14:15], v[30:31], v[32:33]
	ds_bpermute_b32 v30, v26, v16
	ds_bpermute_b32 v31, v26, v17
	v_mov_b32_e32 v26, v7
	v_mov_b32_e32 v7, v8
	s_waitcnt lgkmcnt(0)
	v_pk_mul_f32 v[26:27], v[26:27], v[30:31]
	s_nop 0
	v_cndmask_b32_e64 v9, v27, -v27, s[0:1]
	v_cndmask_b32_e64 v8, v26, -v26, s[0:1]
	v_pk_fma_f32 v[16:17], v[16:17], v[6:7], v[8:9]

; DEVI void ph_prep(const int wv, const Params& p, int l, int nrows_pool, unsigned char* lds_raw) {
;     ...
;             if (hh >= 8) {
;                 float ss = 0.f;
; #pragma unroll
;                 for (int e = 0; e < 8; ++e) ss += v[e] * v[e];
;                 ss += __shfl_xor(ss, 1); ss += __shfl_xor(ss, 2); ss += __shfl_xor(ss, 4);
;                 const float rstd = rsqrtf(ss * (1.0f / 64.0f) + EPS) * (hh >= 10 ? 0.125f * 1.4426950408889634f : 1.0f);
;                 const float* wp = p.in[hh < 10 ? 13 : 12] + l * 64 + d0;
;                 const f32x4 w0 = *(const f32x4*)wp, w1 = *(const f32x4*)(wp + 4);
; #pragma unroll
;                 for (int e = 0; e < 4; ++e) { v[e] *= rstd * w0[e]; v[4 + e] *= rstd * w1[e]; }
;                 if (lat) { const int pp = (sub & 4) ? (pos & 63) : (pos >> 6); const float* cp = ATf + (size_t)(pp * 16 + (d0 & 15)) * 2; const bool up = (sub & 2) != 0;
; #pragma unroll
;                     for (int e = 0; e < 8; ++e) { const float o = __shfl_xor(v[e], 2); const float cc = cp[2 * e], sn = cp[2 * e + 1]; v[e] = up ? o * sn + v[e] * cc : v[e] * cc - o * sn; } }
.LBB0_466:
	s_andn2_saveexec_b64 s[6:7], s[8:9]
	s_cbranch_execz .LBB0_381
	v_pk_mul_f32 v[2:3], v[6:7], v[6:7]
	v_pk_mul_f32 v[4:5], v[8:9], v[8:9]
	v_add_f32_e32 v2, v2, v3
	v_add_f32_e32 v2, v4, v2
	v_pk_mul_f32 v[16:17], v[10:11], v[10:11]
	v_add_f32_e32 v2, v5, v2
	v_add_f32_e32 v2, v16, v2
	v_xor_b32_e32 v3, 1, v225
	v_pk_mul_f32 v[22:23], v[12:13], v[12:13]
	v_add_f32_e32 v2, v17, v2
	v_cmp_lt_i32_e64 s[2:3], v3, v226
	v_add_f32_e32 v2, v22, v2
	v_add_f32_e32 v2, v23, v2
	v_cndmask_b32_e64 v3, v225, v3, s[2:3]
	v_lshlrev_b32_e32 v3, 2, v3
	ds_bpermute_b32 v3, v3, v2
	v_mov_b32_e32 v4, s87
	s_waitcnt lgkmcnt(0)
	v_add_f32_e32 v2, v2, v3
	v_xor_b32_e32 v3, 2, v225
	v_cmp_lt_i32_e64 s[2:3], v3, v226
	s_nop 1
	v_cndmask_b32_e64 v3, v225, v3, s[2:3]
	v_lshlrev_b32_e32 v14, 2, v3
	ds_bpermute_b32 v3, v14, v2
	s_waitcnt lgkmcnt(0)
	v_add_f32_e32 v2, v2, v3
	v_xor_b32_e32 v3, 4, v225
	v_cmp_lt_i32_e64 s[2:3], v3, v226
	s_nop 1
	v_cndmask_b32_e64 v3, v225, v3, s[2:3]
	v_lshlrev_b32_e32 v3, 2, v3
	ds_bpermute_b32 v3, v3, v2
	s_mov_b32 s2, 0x800000
	s_waitcnt lgkmcnt(0)
	v_add_f32_e32 v2, v2, v3
	v_fmamk_f32 v2, v2, 0x3c800000, v196
	v_cmp_gt_f32_e64 s[2:3], s2, v2
	v_mul_f32_e32 v3, 0x4b800000, v2
	s_nop 0
	v_cndmask_b32_e64 v2, v2, v3, s[2:3]
	v_rsq_f32_e32 v2, v2
	s_nop 0
	v_mul_f32_e32 v3, 0x45800000, v2
	v_cndmask_b32_e64 v2, v2, v3, s[2:3]
	v_cmp_lt_u32_e64 s[2:3], 9, v44
	s_nop 1
	v_cndmask_b32_e64 v3, 1.0, v231, s[2:3]
	v_mul_f32_e32 v2, v3, v2
	v_cmp_gt_u32_e64 s[2:3], 10, v44
	v_mov_b32_e32 v3, s85
	s_nop 0
	v_cndmask_b32_e64 v5, v3, v4, s[2:3]
	v_mov_b32_e32 v3, s84
	v_mov_b32_e32 v4, s86
	v_cndmask_b32_e64 v4, v3, v4, s[2:3]
	v_lshl_add_u64 v[4:5], s[18:19], 2, v[4:5]
	v_lshl_add_u64 v[4:5], v[4:5], 0, v[0:1]
	v_mov_b32_e32 v30, v74
	v_mov_b32_e32 v31, v75
	v_mov_b32_e32 v32, v76
	v_mov_b32_e32 v33, v77
	v_mov_b32_e32 v34, v70
	v_mov_b32_e32 v35, v71
	v_mov_b32_e32 v36, v72
	v_mov_b32_e32 v37, v73
	s_waitcnt vmcnt(0)
	v_pk_mul_f32 v[4:5], v[34:35], v[2:3] op_sel_hi:[1,0]
	s_nop 0
	v_pk_mul_f32 v[6:7], v[4:5], v[6:7]
	v_pk_mul_f32 v[4:5], v[30:31], v[2:3] op_sel_hi:[1,0]
	s_nop 0
	v_pk_mul_f32 v[10:11], v[4:5], v[10:11]
	v_pk_mul_f32 v[4:5], v[36:37], v[2:3] op_sel_hi:[1,0]
	v_pk_mul_f32 v[2:3], v[32:33], v[2:3] op_sel_hi:[1,0]
	v_pk_mul_f32 v[8:9], v[4:5], v[8:9]
	v_pk_mul_f32 v[12:13], v[2:3], v[12:13]
	s_and_saveexec_b64 s[2:3], s[4:5]
	s_cbranch_execz .LBB0_380
	v_and_b32_e32 v0, 63, v43
	v_lshrrev_b32_e32 v2, 6, v15
	v_cndmask_b32_e32 v0, v0, v2, vcc
	v_lshlrev_b32_e32 v2, 2, v42
	v_readlane_b32 s4, v252, 19
	v_lshl_or_b32 v0, v0, 7, v2
	v_readlane_b32 s5, v252, 20
	s_nop 4
	global_load_dwordx4 v[2:5], v0, s[4:5] offset:48
	global_load_dwordx4 v[30:33], v0, s[4:5] offset:32
	global_load_dwordx4 v[34:37], v0, s[4:5] offset:16
	global_load_dwordx4 v[38:41], v0, s[4:5]
	ds_bpermute_b32 v16, v14, v6
	ds_bpermute_b32 v17, v14, v7
	s_waitcnt vmcnt(3)
	v_mov_b32_e32 v15, v5
	s_waitcnt vmcnt(0)
	v_mov_b32_e32 v22, v39
	v_mov_b32_e32 v23, v41
	s_waitcnt lgkmcnt(0)
	v_pk_mul_f32 v[16:17], v[22:23], v[16:17]
	v_mov_b32_e32 v39, v40
	v_cndmask_b32_e64 v17, v17, -v17, s[0:1]
	v_cndmask_b32_e64 v16, v16, -v16, s[0:1]
	v_pk_fma_f32 v[6:7], v[6:7], v[38:39], v[16:17]
	ds_bpermute_b32 v16, v14, v8
	ds_bpermute_b32 v17, v14, v9
	v_mov_b32_e32 v22, v35
	v_mov_b32_e32 v23, v37
	v_mov_b32_e32 v35, v36
	s_waitcnt lgkmcnt(0)
	v_pk_mul_f32 v[16:17], v[22:23], v[16:17]
	s_nop 0
	v_cndmask_b32_e64 v17, v17, -v17, s[0:1]
	v_cndmask_b32_e64 v16, v16, -v16, s[0:1]
	v_pk_fma_f32 v[8:9], v[8:9], v[34:35], v[16:17]
	ds_bpermute_b32 v16, v14, v10
	ds_bpermute_b32 v17, v14, v11
	v_mov_b32_e32 v22, v31
	v_mov_b32_e32 v23, v33
	v_mov_b32_e32 v31, v32
	s_waitcnt lgkmcnt(0)
	v_pk_mul_f32 v[16:17], v[22:23], v[16:17]
	s_nop 0
	v_cndmask_b32_e64 v17, v17, -v17, s[0:1]
	v_cndmask_b32_e64 v16, v16, -v16, s[0:1]
	v_pk_fma_f32 v[10:11], v[10:11], v[30:31], v[16:17]
	ds_bpermute_b32 v16, v14, v12
	ds_bpermute_b32 v17, v14, v13
	v_mov_b32_e32 v14, v3
	v_mov_b32_e32 v3, v4
	s_waitcnt lgkmcnt(0)
	v_pk_mul_f32 v[14:15], v[14:15], v[16:17]
	s_nop 0
	v_cndmask_b32_e64 v5, v15, -v15, s[0:1]
	v_cndmask_b32_e64 v4, v14, -v14, s[0:1]
	v_pk_fma_f32 v[12:13], v[12:13], v[2:3], v[4:5]
	s_branch .LBB0_380
